# scan: output stores deferred to next step's P1/P2 (full phase to drain)
# baseline (speedup 1.0000x reference)
.LBB0_487:
	s_and_b64 vcc, exec, s[0:1]
	s_cbranch_vccz .LBB0_397
	s_setprio 3
	v_mov_b64_e32 v[4:5], s[16:17]
	flat_load_dwordx2 v[100:101], v[4:5]
	s_lshl_b32 s4, s75, 6
	s_and_b32 s0, s75, 1
	s_ashr_i32 s1, s75, 3
	s_and_b32 s4, s4, 0xffffff80
	s_ashr_i32 s5, s4, 31
	s_mul_i32 s8, s1, 0x3800000
	s_lshl_b32 s9, s0, 7
	s_lshl_b32 s18, s0, 13
	s_lshl_b32 s10, s75, 7
	s_and_b32 s10, s10, 0x300
	s_add_i32 s8, s8, s9
	s_add_i32 s8, s8, s10
	v_and_b32_e32 v22, 63, v198
	v_mov_b32_e32 v23, 0
	v_lshrrev_b32_e32 v24, 6, v198
	v_mov_b32_e32 v25, 0
	v_and_b32_e32 v26, 15, v198
	v_bfe_u32 v27, v198, 4, 2
	v_lshl_add_u32 v2, v22, 4, 0
	v_lshlrev_b32_e32 v131, 11, v24
	v_lshl_add_u32 v131, v22, 3, v131
	v_mul_u32_u24_e32 v114, 0x7000, v27
	v_lshl_add_u32 v114, v24, 5, v114
	v_lshl_add_u32 v114, v26, 1, v114
	v_add_u32_e32 v114, s8, v114
	s_nop 0
	v_readfirstlane_b32 s93, v24
	s_mov_b64 s[94:95], 0x400
	s_mov_b64 s[96:97], 0x800
	s_mov_b64 s[78:79], 0xc00
	s_lshl_b32 s88, s93, 12
	s_add_i32 s89, s88, 0x4000
	s_add_i32 s90, s88, 0x8000
	s_lshl_b32 s91, s93, 11
	s_add_i32 s92, s91, 0xe000
	s_add_i32 s91, s91, 0xc000
	s_lshl_b64 s[0:1], s[4:5], 2
	s_add_u32 s0, s0, 0x2ce00000
	s_addc_u32 s1, s1, 0
	s_movk_i32 s6, 0x7f
	v_mov_b32_e32 v4, 0
	v_mov_b32_e32 v5, v4
	v_mov_b32_e32 v6, v4
	v_mov_b32_e32 v7, v4
	v_mov_b32_e32 v16, v4
	v_mov_b32_e32 v17, v4
	v_mov_b32_e32 v18, v4
	v_mov_b32_e32 v19, v4
	v_mov_b32_e32 v44, v4
	v_mov_b32_e32 v45, v4
	v_mov_b32_e32 v46, v4
	v_mov_b32_e32 v47, v4
	v_mov_b32_e32 v76, v4
	v_mov_b32_e32 v77, v4
	v_mov_b32_e32 v78, v4
	v_mov_b32_e32 v79, v4
	v_mov_b32_e32 v84, v4
	v_mov_b32_e32 v85, v4
	v_mov_b32_e32 v86, v4
	v_mov_b32_e32 v87, v4
	v_mov_b32_e32 v88, v4
	v_mov_b32_e32 v89, v4
	v_mov_b32_e32 v90, v4
	v_mov_b32_e32 v91, v4
	v_mov_b32_e32 v92, v4
	v_mov_b32_e32 v93, v4
	v_mov_b32_e32 v94, v4
	v_mov_b32_e32 v95, v4
	v_mov_b32_e32 v96, v4
	v_mov_b32_e32 v97, v4
	v_mov_b32_e32 v98, v4
	v_mov_b32_e32 v99, v4
	s_waitcnt vmcnt(0) lgkmcnt(0)
	v_readfirstlane_b32 s86, v100
	v_readfirstlane_b32 s87, v101
	v_mad_i64_i32 v[28:29], s[10:11], s4, v210, v[100:101]
	v_lshl_add_u64 v[28:29], v[28:29], 0, s[34:35]
	v_lshl_add_u64 v[28:29], v[22:23], 4, v[28:29]
	v_lshlrev_b32_e32 v32, 12, v24
	v_mov_b32_e32 v33, 0
	v_lshl_add_u64 v[8:9], v[32:33], 0, v[28:29]
	s_mov_b64 s[10:11], 0x4000
	v_lshl_add_u64 v[10:11], v[8:9], 0, s[10:11]
	s_mov_b64 s[10:11], 0x8000
	v_lshl_add_u64 v[12:13], v[8:9], 0, s[10:11]
	v_lshlrev_b32_e32 v32, 11, v24
	v_lshl_add_u64 v[14:15], v[32:33], 0, v[28:29]
	s_add_u32 s10, s18, 0xe000
	s_mov_b32 s11, 0
	v_lshl_add_u64 v[20:21], v[14:15], 0, s[10:11]
	s_mov_b64 s[10:11], 0xc000
	v_lshl_add_u64 v[14:15], v[14:15], 0, s[10:11]
	v_lshl_add_u64 v[32:33], v[100:101], 0, s[0:1]
	v_lshl_add_u64 v[32:33], v[22:23], 2, v[32:33]
	global_load_dword v34, v[32:33], off
	global_load_dword v35, v[32:33], off offset:256
	s_mov_b32 m0, s88
	s_nop 0
	global_load_lds_dwordx4 v[8:9], off
	s_add_i32 m0, s88, 0x400
	v_lshl_add_u64 v[30:31], v[8:9], 0, s[94:95]
	global_load_lds_dwordx4 v[30:31], off
	s_add_i32 m0, s88, 0x800
	v_lshl_add_u64 v[30:31], v[8:9], 0, s[96:97]
	global_load_lds_dwordx4 v[30:31], off
	s_add_i32 m0, s88, 0xc00
	v_lshl_add_u64 v[30:31], v[8:9], 0, s[78:79]
	global_load_lds_dwordx4 v[30:31], off
	s_mov_b32 m0, s92
	s_nop 0
	global_load_lds_dwordx4 v[20:21], off
	s_add_i32 m0, s92, 0x400
	v_lshl_add_u64 v[30:31], v[20:21], 0, s[94:95]
	global_load_lds_dwordx4 v[30:31], off
	s_mov_b32 m0, s89
	s_nop 0
	global_load_lds_dwordx4 v[10:11], off
	s_add_i32 m0, s89, 0x400
	v_lshl_add_u64 v[30:31], v[10:11], 0, s[94:95]
	global_load_lds_dwordx4 v[30:31], off
	s_add_i32 m0, s89, 0x800
	v_lshl_add_u64 v[30:31], v[10:11], 0, s[96:97]
	global_load_lds_dwordx4 v[30:31], off
	s_add_i32 m0, s89, 0xc00
	v_lshl_add_u64 v[30:31], v[10:11], 0, s[78:79]
	global_load_lds_dwordx4 v[30:31], off
	s_mov_b32 m0, s91
	s_nop 0
	global_load_lds_dwordx4 v[14:15], off
	s_add_i32 m0, s91, 0x400
	v_lshl_add_u64 v[30:31], v[14:15], 0, s[94:95]
	global_load_lds_dwordx4 v[30:31], off
	s_mov_b32 m0, s90
	s_nop 0
	global_load_lds_dwordx4 v[12:13], off
	s_add_i32 m0, s90, 0x400
	v_lshl_add_u64 v[30:31], v[12:13], 0, s[94:95]
	global_load_lds_dwordx4 v[30:31], off
	s_add_i32 m0, s90, 0x800
	v_lshl_add_u64 v[30:31], v[12:13], 0, s[96:97]
	global_load_lds_dwordx4 v[30:31], off
	s_add_i32 m0, s90, 0xc00
	v_lshl_add_u64 v[30:31], v[12:13], 0, s[78:79]
	global_load_lds_dwordx4 v[30:31], off
	v_lshl_add_u64 v[8:9], v[8:9], 0, s[50:51]
	v_lshl_add_u64 v[10:11], v[10:11], 0, s[50:51]
	v_lshl_add_u64 v[12:13], v[12:13], 0, s[50:51]
	v_lshl_add_u64 v[14:15], v[14:15], 0, s[50:51]
	v_lshl_add_u64 v[20:21], v[20:21], 0, s[50:51]
	s_waitcnt vmcnt(0)
	s_barrier
.Lsc_step:
	ds_read_b128 v[212:215], v2
	ds_read_b128 v[216:219], v2 offset:4096
	ds_read_b128 v[220:223], v2 offset:8192
	ds_read_b128 v[224:227], v2 offset:12288
	ds_read_b128 v[228:231], v2 offset:1024
	ds_read2st64_b64 v[188:191], v131 offset0:112 offset1:113
	ds_read2st64_b64 v[192:195], v131 offset0:114 offset1:115
	v_cvt_pk_bf16_f32 v132, v16, v17
	v_cvt_pk_bf16_f32 v133, v18, v19
	v_cvt_pk_bf16_f32 v134, v4, v5
	v_cvt_pk_bf16_f32 v135, v6, v7
	v_cvt_pk_bf16_f32 v136, v44, v45
	v_cvt_pk_bf16_f32 v137, v46, v47
	v_cvt_pk_bf16_f32 v138, v76, v77
	v_cvt_pk_bf16_f32 v139, v78, v79
	v_cvt_pk_bf16_f32 v140, v84, v85
	v_cvt_pk_bf16_f32 v141, v86, v87
	v_cvt_pk_bf16_f32 v142, v88, v89
	v_cvt_pk_bf16_f32 v143, v90, v91
	v_cvt_pk_bf16_f32 v144, v92, v93
	v_cvt_pk_bf16_f32 v145, v94, v95
	v_cvt_pk_bf16_f32 v146, v96, v97
	v_cvt_pk_bf16_f32 v147, v98, v99
	v_add_u32_e32 v197, 0x3f90c00, v114
	s_cmp_eq_u32 s6, 0x7f
	s_cbranch_scc1 .Lsc_nost1
	global_store_short_d16_hi v197, v48, s[86:87]
	v_add_u32_e32 v65, 0x1c00, v197
	global_store_short_d16_hi v65, v49, s[86:87]
	v_add_u32_e32 v66, 0x3800, v197
	global_store_short_d16_hi v66, v50, s[86:87]
	v_add_u32_e32 v67, 0x5400, v197
	global_store_short_d16_hi v67, v51, s[86:87]
	v_add_u32_e32 v68, 0x1c000, v197
	global_store_short_d16_hi v68, v52, s[86:87]
	v_add_u32_e32 v69, 0x1dc00, v197
	global_store_short_d16_hi v69, v53, s[86:87]
	v_add_u32_e32 v70, 0x1f800, v197
	global_store_short_d16_hi v70, v54, s[86:87]
	v_add_u32_e32 v71, 0x21400, v197
	global_store_short_d16_hi v71, v55, s[86:87]
.Lsc_nost1:
	s_waitcnt lgkmcnt(6)
	v_mfma_f32_16x16x32_bf16 v[156:159], v[212:215], v[132:135], 0
	ds_read_b128 v[232:235], v2 offset:5120
	s_waitcnt lgkmcnt(6)
	v_mfma_f32_16x16x32_bf16 v[160:163], v[216:219], v[132:135], 0
	ds_read_b128 v[236:239], v2 offset:9216
	s_waitcnt lgkmcnt(6)
	v_mfma_f32_16x16x32_bf16 v[164:167], v[220:223], v[132:135], 0
	ds_read_b128 v[212:215], v2 offset:13312
	s_waitcnt lgkmcnt(6)
	v_mfma_f32_16x16x32_bf16 v[168:171], v[224:227], v[132:135], 0
	ds_read_b128 v[216:219], v2 offset:2048
	s_waitcnt lgkmcnt(6)
	v_mfma_f32_16x16x32_bf16 v[156:159], v[228:231], v[136:139], v[156:159]
	ds_read_b128 v[220:223], v2 offset:6144
	s_waitcnt lgkmcnt(4)
	v_mfma_f32_16x16x32_bf16 v[160:163], v[232:235], v[136:139], v[160:163]
	ds_read_b128 v[224:227], v2 offset:10240
	s_waitcnt lgkmcnt(4)
	v_mfma_f32_16x16x32_bf16 v[164:167], v[236:239], v[136:139], v[164:167]
	ds_read_b128 v[228:231], v2 offset:14336
	s_waitcnt lgkmcnt(4)
	v_mfma_f32_16x16x32_bf16 v[168:171], v[212:215], v[136:139], v[168:171]
	ds_read_b128 v[232:235], v2 offset:3072
	s_waitcnt lgkmcnt(4)
	v_mfma_f32_16x16x32_bf16 v[156:159], v[216:219], v[140:143], v[156:159]
	ds_read_b128 v[236:239], v2 offset:7168
	s_waitcnt lgkmcnt(4)
	v_mfma_f32_16x16x32_bf16 v[160:163], v[220:223], v[140:143], v[160:163]
	ds_read_b128 v[212:215], v2 offset:11264
	s_waitcnt lgkmcnt(4)
	v_mfma_f32_16x16x32_bf16 v[164:167], v[224:227], v[140:143], v[164:167]
	ds_read_b128 v[216:219], v2 offset:15360
	s_waitcnt lgkmcnt(4)
	v_mfma_f32_16x16x32_bf16 v[168:171], v[228:231], v[140:143], v[168:171]
	s_waitcnt lgkmcnt(3)
	v_mfma_f32_16x16x32_bf16 v[156:159], v[232:235], v[144:147], v[156:159]
	s_waitcnt lgkmcnt(2)
	v_mfma_f32_16x16x32_bf16 v[160:163], v[236:239], v[144:147], v[160:163]
	s_waitcnt lgkmcnt(1)
	v_mfma_f32_16x16x32_bf16 v[164:167], v[212:215], v[144:147], v[164:167]
	s_waitcnt lgkmcnt(0)
	v_mfma_f32_16x16x32_bf16 v[168:171], v[216:219], v[144:147], v[168:171]
	s_waitcnt lgkmcnt(0)
	s_waitcnt vmcnt(0)
	s_barrier
	s_cmp_eq_u32 s6, 0
	s_cbranch_scc1 .Lsc_skip1
	s_mov_b32 m0, s88
	s_nop 0
	global_load_lds_dwordx4 v[8:9], off
	s_add_i32 m0, s88, 0x400
	v_lshl_add_u64 v[30:31], v[8:9], 0, s[94:95]
	global_load_lds_dwordx4 v[30:31], off
	s_add_i32 m0, s88, 0x800
	v_lshl_add_u64 v[30:31], v[8:9], 0, s[96:97]
	global_load_lds_dwordx4 v[30:31], off
	s_add_i32 m0, s88, 0xc00
	v_lshl_add_u64 v[30:31], v[8:9], 0, s[78:79]
	global_load_lds_dwordx4 v[30:31], off
	s_mov_b32 m0, s92
	s_nop 0
	global_load_lds_dwordx4 v[20:21], off
	s_add_i32 m0, s92, 0x400
	v_lshl_add_u64 v[30:31], v[20:21], 0, s[94:95]
	global_load_lds_dwordx4 v[30:31], off
.Lsc_skip1:
	ds_read_b128 v[220:223], v2 offset:16384
	ds_read_b128 v[224:227], v2 offset:20480
	ds_read_b128 v[228:231], v2 offset:24576
	ds_read_b128 v[232:235], v2 offset:28672
	ds_read_b128 v[236:239], v2 offset:17408
	s_sub_i32 s10, 0x7f, s6
	s_and_b32 s11, s10, 63
	v_readlane_b32 s7, v34, s11
	v_readlane_b32 s9, v35, s11
	s_nop 1
	s_cmp_lt_u32 s10, 64
	s_cselect_b32 s7, s7, s9
	v_mov_b32_e32 v196, s7
	s_cmp_eq_u32 s6, 0x7f
	s_cbranch_scc1 .Lsc_nost2
	v_add_u32_e32 v64, 0x38000, v197
	global_store_short_d16_hi v64, v56, s[86:87]
	v_add_u32_e32 v65, 0x39c00, v197
	global_store_short_d16_hi v65, v57, s[86:87]
	v_add_u32_e32 v66, 0x3b800, v197
	global_store_short_d16_hi v66, v58, s[86:87]
	v_add_u32_e32 v67, 0x3d400, v197
	global_store_short_d16_hi v67, v59, s[86:87]
	v_add_u32_e32 v68, 0x54000, v197
	global_store_short_d16_hi v68, v60, s[86:87]
	v_add_u32_e32 v69, 0x55c00, v197
	global_store_short_d16_hi v69, v61, s[86:87]
	v_add_u32_e32 v70, 0x57800, v197
	global_store_short_d16_hi v70, v62, s[86:87]
	v_add_u32_e32 v71, 0x59400, v197
	global_store_short_d16_hi v71, v63, s[86:87]
.Lsc_nost2:
	s_waitcnt lgkmcnt(4)
	v_mfma_f32_16x16x32_bf16 v[172:175], v[220:223], v[132:135], 0
	ds_read_b128 v[212:215], v2 offset:21504
	v_pk_mul_f32 v[16:17], v[16:17], v[196:197] op_sel_hi:[1,0]
	v_pk_mul_f32 v[18:19], v[18:19], v[196:197] op_sel_hi:[1,0]
	s_waitcnt lgkmcnt(4)
	v_mfma_f32_16x16x32_bf16 v[176:179], v[224:227], v[132:135], 0
	ds_read_b128 v[216:219], v2 offset:25600
	v_pk_mul_f32 v[4:5], v[4:5], v[196:197] op_sel_hi:[1,0]
	v_pk_mul_f32 v[6:7], v[6:7], v[196:197] op_sel_hi:[1,0]
	s_waitcnt lgkmcnt(4)
	v_mfma_f32_16x16x32_bf16 v[180:183], v[228:231], v[132:135], 0
	ds_read_b128 v[220:223], v2 offset:29696
	v_pk_mul_f32 v[44:45], v[44:45], v[196:197] op_sel_hi:[1,0]
	v_pk_mul_f32 v[46:47], v[46:47], v[196:197] op_sel_hi:[1,0]
	v_lshlrev_b32_e32 v240, 16, v188
	v_and_b32_e32 v241, 0xffff0000, v188
	v_lshlrev_b32_e32 v242, 16, v189
	v_and_b32_e32 v243, 0xffff0000, v189
	s_waitcnt lgkmcnt(4)
	v_mfma_f32_16x16x32_bf16 v[184:187], v[232:235], v[132:135], 0
	ds_read_b128 v[224:227], v2 offset:18432
	v_pk_mul_f32 v[76:77], v[76:77], v[196:197] op_sel_hi:[1,0]
	v_pk_mul_f32 v[78:79], v[78:79], v[196:197] op_sel_hi:[1,0]
	v_sub_f32_e32 v156, v240, v156
	v_sub_f32_e32 v157, v241, v157
	v_sub_f32_e32 v158, v242, v158
	v_sub_f32_e32 v159, v243, v159
	s_waitcnt lgkmcnt(4)
	v_mfma_f32_16x16x32_bf16 v[172:175], v[236:239], v[136:139], v[172:175]
	ds_read_b128 v[228:231], v2 offset:22528
	v_pk_mul_f32 v[84:85], v[84:85], v[196:197] op_sel_hi:[1,0]
	v_pk_mul_f32 v[86:87], v[86:87], v[196:197] op_sel_hi:[1,0]
	v_lshlrev_b32_e32 v240, 16, v190
	v_and_b32_e32 v241, 0xffff0000, v190
	v_lshlrev_b32_e32 v242, 16, v191
	v_and_b32_e32 v243, 0xffff0000, v191
	s_waitcnt lgkmcnt(4)
	v_mfma_f32_16x16x32_bf16 v[176:179], v[212:215], v[136:139], v[176:179]
	ds_read_b128 v[232:235], v2 offset:26624
	v_pk_mul_f32 v[88:89], v[88:89], v[196:197] op_sel_hi:[1,0]
	v_pk_mul_f32 v[90:91], v[90:91], v[196:197] op_sel_hi:[1,0]
	v_sub_f32_e32 v160, v240, v160
	v_sub_f32_e32 v161, v241, v161
	v_sub_f32_e32 v162, v242, v162
	v_sub_f32_e32 v163, v243, v163
	s_waitcnt lgkmcnt(4)
	v_mfma_f32_16x16x32_bf16 v[180:183], v[216:219], v[136:139], v[180:183]
	ds_read_b128 v[236:239], v2 offset:30720
	v_pk_mul_f32 v[92:93], v[92:93], v[196:197] op_sel_hi:[1,0]
	v_pk_mul_f32 v[94:95], v[94:95], v[196:197] op_sel_hi:[1,0]
	v_lshlrev_b32_e32 v240, 16, v192
	v_and_b32_e32 v241, 0xffff0000, v192
	v_lshlrev_b32_e32 v242, 16, v193
	v_and_b32_e32 v243, 0xffff0000, v193
	v_cvt_pk_bf16_f32 v148, v156, v157
	v_cvt_pk_bf16_f32 v149, v158, v159
	v_cvt_pk_bf16_f32 v150, v160, v161
	v_cvt_pk_bf16_f32 v151, v162, v163
	s_waitcnt lgkmcnt(4)
	v_mfma_f32_16x16x32_bf16 v[184:187], v[220:223], v[136:139], v[184:187]
	ds_read_b128 v[212:215], v2 offset:19456
	v_pk_mul_f32 v[96:97], v[96:97], v[196:197] op_sel_hi:[1,0]
	v_pk_mul_f32 v[98:99], v[98:99], v[196:197] op_sel_hi:[1,0]
	v_sub_f32_e32 v164, v240, v164
	v_sub_f32_e32 v165, v241, v165
	v_sub_f32_e32 v166, v242, v166
	v_sub_f32_e32 v167, v243, v167
	s_waitcnt lgkmcnt(4)
	v_mfma_f32_16x16x32_bf16 v[172:175], v[224:227], v[140:143], v[172:175]
	ds_read_b128 v[216:219], v2 offset:23552
	v_lshlrev_b32_e32 v240, 16, v194
	v_and_b32_e32 v241, 0xffff0000, v194
	v_lshlrev_b32_e32 v242, 16, v195
	v_and_b32_e32 v243, 0xffff0000, v195
	s_waitcnt lgkmcnt(4)
	v_mfma_f32_16x16x32_bf16 v[176:179], v[228:231], v[140:143], v[176:179]
	ds_read_b128 v[220:223], v2 offset:27648
	v_sub_f32_e32 v168, v240, v168
	v_sub_f32_e32 v169, v241, v169
	v_sub_f32_e32 v170, v242, v170
	v_sub_f32_e32 v171, v243, v171
	s_waitcnt lgkmcnt(4)
	v_mfma_f32_16x16x32_bf16 v[180:183], v[232:235], v[140:143], v[180:183]
	ds_read_b128 v[224:227], v2 offset:31744
	v_cvt_pk_bf16_f32 v152, v164, v165
	v_cvt_pk_bf16_f32 v153, v166, v167
	v_cvt_pk_bf16_f32 v154, v168, v169
	v_cvt_pk_bf16_f32 v155, v170, v171
	s_waitcnt lgkmcnt(4)
	v_mfma_f32_16x16x32_bf16 v[184:187], v[236:239], v[140:143], v[184:187]
	s_waitcnt lgkmcnt(3)
	v_mfma_f32_16x16x32_bf16 v[172:175], v[212:215], v[144:147], v[172:175]
	s_waitcnt lgkmcnt(2)
	v_mfma_f32_16x16x32_bf16 v[176:179], v[216:219], v[144:147], v[176:179]
	s_waitcnt lgkmcnt(1)
	v_mfma_f32_16x16x32_bf16 v[180:183], v[220:223], v[144:147], v[180:183]
	s_waitcnt lgkmcnt(0)
	v_mfma_f32_16x16x32_bf16 v[184:187], v[224:227], v[144:147], v[184:187]
	s_waitcnt lgkmcnt(0)
	s_cmp_eq_u32 s6, 0
	s_cbranch_scc1 .Lsc_last2
	s_waitcnt vmcnt(0)
	s_barrier
	s_mov_b32 m0, s89
	s_nop 0
	global_load_lds_dwordx4 v[10:11], off
	s_add_i32 m0, s89, 0x400
	v_lshl_add_u64 v[30:31], v[10:11], 0, s[94:95]
	global_load_lds_dwordx4 v[30:31], off
	s_add_i32 m0, s89, 0x800
	v_lshl_add_u64 v[30:31], v[10:11], 0, s[96:97]
	global_load_lds_dwordx4 v[30:31], off
	s_add_i32 m0, s89, 0xc00
	v_lshl_add_u64 v[30:31], v[10:11], 0, s[78:79]
	global_load_lds_dwordx4 v[30:31], off
	s_branch .Lsc_p3

.Lsc_p3:
	ds_read_b128 v[228:231], v2 offset:49152
	ds_read_b128 v[232:235], v2 offset:51200
	ds_read_b128 v[236:239], v2 offset:53248
	ds_read_b128 v[212:215], v2 offset:55296
	ds_read_b128 v[216:219], v2 offset:50176
	s_waitcnt lgkmcnt(4)
	v_mfma_f32_16x16x32_bf16 v[172:175], v[228:231], v[148:151], v[172:175]
	ds_read_b128 v[220:223], v2 offset:52224
	s_waitcnt lgkmcnt(4)
	v_mfma_f32_16x16x32_bf16 v[176:179], v[232:235], v[148:151], v[176:179]
	ds_read_b128 v[224:227], v2 offset:54272
	s_waitcnt lgkmcnt(4)
	v_mfma_f32_16x16x32_bf16 v[180:183], v[236:239], v[148:151], v[180:183]
	ds_read_b128 v[228:231], v2 offset:56320
	s_waitcnt lgkmcnt(4)
	v_mfma_f32_16x16x32_bf16 v[184:187], v[212:215], v[148:151], v[184:187]
	ds_read_b128 v[232:235], v2 offset:32768
	s_waitcnt lgkmcnt(4)
	v_mfma_f32_16x16x32_bf16 v[172:175], v[216:219], v[152:155], v[172:175]
	ds_read_b128 v[236:239], v2 offset:34816
	s_waitcnt lgkmcnt(4)
	v_mfma_f32_16x16x32_bf16 v[176:179], v[220:223], v[152:155], v[176:179]
	ds_read_b128 v[212:215], v2 offset:36864
	s_waitcnt lgkmcnt(4)
	v_mfma_f32_16x16x32_bf16 v[180:183], v[224:227], v[152:155], v[180:183]
	ds_read_b128 v[216:219], v2 offset:38912
	s_waitcnt lgkmcnt(4)
	v_mfma_f32_16x16x32_bf16 v[184:187], v[228:231], v[152:155], v[184:187]
	ds_read_b128 v[220:223], v2 offset:40960
	s_waitcnt lgkmcnt(4)
	v_mfma_f32_16x16x32_bf16 v[16:19], v[232:235], v[148:151], v[16:19]
	ds_read_b128 v[224:227], v2 offset:43008
	s_waitcnt lgkmcnt(4)
	v_mfma_f32_16x16x32_bf16 v[4:7], v[236:239], v[148:151], v[4:7]
	ds_read_b128 v[228:231], v2 offset:45056
	v_bfe_u32 v156, v172, 16, 1
	v_add3_u32 v48, v172, v156, s43
	v_bfe_u32 v157, v173, 16, 1
	v_add3_u32 v49, v173, v157, s43
	s_waitcnt lgkmcnt(4)
	v_mfma_f32_16x16x32_bf16 v[44:47], v[212:215], v[148:151], v[44:47]
	ds_read_b128 v[232:235], v2 offset:47104
	v_bfe_u32 v158, v174, 16, 1
	v_add3_u32 v50, v174, v158, s43
	v_bfe_u32 v159, v175, 16, 1
	v_add3_u32 v51, v175, v159, s43
	s_waitcnt lgkmcnt(4)
	v_mfma_f32_16x16x32_bf16 v[76:79], v[216:219], v[148:151], v[76:79]
	ds_read_b128 v[236:239], v2 offset:33792
	s_waitcnt lgkmcnt(4)
	v_mfma_f32_16x16x32_bf16 v[84:87], v[220:223], v[148:151], v[84:87]
	ds_read_b128 v[212:215], v2 offset:35840
	v_bfe_u32 v160, v176, 16, 1
	v_add3_u32 v52, v176, v160, s43
	v_bfe_u32 v161, v177, 16, 1
	v_add3_u32 v53, v177, v161, s43
	s_waitcnt lgkmcnt(4)
	v_mfma_f32_16x16x32_bf16 v[88:91], v[224:227], v[148:151], v[88:91]
	ds_read_b128 v[216:219], v2 offset:37888
	v_bfe_u32 v162, v178, 16, 1
	v_add3_u32 v54, v178, v162, s43
	v_bfe_u32 v163, v179, 16, 1
	v_add3_u32 v55, v179, v163, s43
	s_waitcnt lgkmcnt(4)
	v_mfma_f32_16x16x32_bf16 v[92:95], v[228:231], v[148:151], v[92:95]
	ds_read_b128 v[220:223], v2 offset:39936
	s_waitcnt lgkmcnt(4)
	v_mfma_f32_16x16x32_bf16 v[96:99], v[232:235], v[148:151], v[96:99]
	ds_read_b128 v[224:227], v2 offset:41984
	v_bfe_u32 v156, v180, 16, 1
	v_add3_u32 v56, v180, v156, s43
	v_bfe_u32 v157, v181, 16, 1
	v_add3_u32 v57, v181, v157, s43
	s_waitcnt lgkmcnt(4)
	v_mfma_f32_16x16x32_bf16 v[16:19], v[236:239], v[152:155], v[16:19]
	ds_read_b128 v[228:231], v2 offset:44032
	v_bfe_u32 v158, v182, 16, 1
	v_add3_u32 v58, v182, v158, s43
	v_bfe_u32 v159, v183, 16, 1
	v_add3_u32 v59, v183, v159, s43
	s_waitcnt lgkmcnt(4)
	v_mfma_f32_16x16x32_bf16 v[4:7], v[212:215], v[152:155], v[4:7]
	ds_read_b128 v[232:235], v2 offset:46080
	s_waitcnt lgkmcnt(4)
	v_mfma_f32_16x16x32_bf16 v[44:47], v[216:219], v[152:155], v[44:47]
	ds_read_b128 v[236:239], v2 offset:48128
	v_bfe_u32 v160, v184, 16, 1
	v_add3_u32 v60, v184, v160, s43
	v_bfe_u32 v161, v185, 16, 1
	v_add3_u32 v61, v185, v161, s43
	s_waitcnt lgkmcnt(4)
	v_mfma_f32_16x16x32_bf16 v[76:79], v[220:223], v[152:155], v[76:79]
	v_bfe_u32 v162, v186, 16, 1
	v_add3_u32 v62, v186, v162, s43
	v_bfe_u32 v163, v187, 16, 1
	v_add3_u32 v63, v187, v163, s43
	s_waitcnt lgkmcnt(3)
	v_mfma_f32_16x16x32_bf16 v[84:87], v[224:227], v[152:155], v[84:87]
	s_waitcnt lgkmcnt(2)
	v_mfma_f32_16x16x32_bf16 v[88:91], v[228:231], v[152:155], v[88:91]
	s_waitcnt lgkmcnt(1)
	v_mfma_f32_16x16x32_bf16 v[92:95], v[232:235], v[152:155], v[92:95]
	s_waitcnt lgkmcnt(0)
	v_mfma_f32_16x16x32_bf16 v[96:99], v[236:239], v[152:155], v[96:99]
	s_waitcnt lgkmcnt(0)
	s_waitcnt vmcnt(0)
	s_barrier
	s_cmp_eq_u32 s6, 0
	s_cbranch_scc1 .Lsc_exit
	s_mov_b32 m0, s91
	s_nop 0
	global_load_lds_dwordx4 v[14:15], off
	s_add_i32 m0, s91, 0x400
	v_lshl_add_u64 v[30:31], v[14:15], 0, s[94:95]
	global_load_lds_dwordx4 v[30:31], off
	s_mov_b32 m0, s90
	s_nop 0
	global_load_lds_dwordx4 v[12:13], off
	s_add_i32 m0, s90, 0x400
	v_lshl_add_u64 v[30:31], v[12:13], 0, s[94:95]
	global_load_lds_dwordx4 v[30:31], off
	s_add_i32 m0, s90, 0x800
	v_lshl_add_u64 v[30:31], v[12:13], 0, s[96:97]
	global_load_lds_dwordx4 v[30:31], off
	s_add_i32 m0, s90, 0xc00
	v_lshl_add_u64 v[30:31], v[12:13], 0, s[78:79]
	global_load_lds_dwordx4 v[30:31], off
	s_add_u32 s0, s0, 4
	s_addc_u32 s1, s1, 0
	s_add_i32 s6, s6, -1
	v_add_u32_e32 v114, 0x70000, v114
	v_lshl_add_u64 v[8:9], v[8:9], 0, s[50:51]
	v_lshl_add_u64 v[10:11], v[10:11], 0, s[50:51]
	v_lshl_add_u64 v[12:13], v[12:13], 0, s[50:51]
	v_lshl_add_u64 v[14:15], v[14:15], 0, s[50:51]
	v_lshl_add_u64 v[20:21], v[20:21], 0, s[50:51]
	s_branch .Lsc_step
.Lsc_exit:
	v_add_u32_e32 v197, 0x4000c00, v114
	global_store_short_d16_hi v197, v48, s[86:87]
	v_add_u32_e32 v65, 0x1c00, v197
	global_store_short_d16_hi v65, v49, s[86:87]
	v_add_u32_e32 v66, 0x3800, v197
	global_store_short_d16_hi v66, v50, s[86:87]
	v_add_u32_e32 v67, 0x5400, v197
	global_store_short_d16_hi v67, v51, s[86:87]
	v_add_u32_e32 v68, 0x1c000, v197
	global_store_short_d16_hi v68, v52, s[86:87]
	v_add_u32_e32 v69, 0x1dc00, v197
	global_store_short_d16_hi v69, v53, s[86:87]
	v_add_u32_e32 v70, 0x1f800, v197
	global_store_short_d16_hi v70, v54, s[86:87]
	v_add_u32_e32 v71, 0x21400, v197
	global_store_short_d16_hi v71, v55, s[86:87]
	v_add_u32_e32 v64, 0x38000, v197
	global_store_short_d16_hi v64, v56, s[86:87]
	v_add_u32_e32 v65, 0x39c00, v197
	global_store_short_d16_hi v65, v57, s[86:87]
	v_add_u32_e32 v66, 0x3b800, v197
	global_store_short_d16_hi v66, v58, s[86:87]
	v_add_u32_e32 v67, 0x3d400, v197
	global_store_short_d16_hi v67, v59, s[86:87]
	v_add_u32_e32 v68, 0x54000, v197
	global_store_short_d16_hi v68, v60, s[86:87]
	v_add_u32_e32 v69, 0x55c00, v197
	global_store_short_d16_hi v69, v61, s[86:87]
	v_add_u32_e32 v70, 0x57800, v197
	global_store_short_d16_hi v70, v62, s[86:87]
	v_add_u32_e32 v71, 0x59400, v197
	global_store_short_d16_hi v71, v63, s[86:87]
	s_branch .LBB0_397
